# operand prep split at chunk granularity: P2b prepares one 16-token chunk per WG (chunks 0..255), the other 768 chunks run on the non-scan WGs during the scan with per-chunk release flags
# baseline (speedup 1.0000x reference)
; #define LAS __attribute__((address_space(3)))
; __device__ __forceinline__ v2u pk4(f32x4 v) { v2u o; o.x = pk2(v.x, v.y); o.y = pk2(v.z, v.w); return o; }
; __device__ __forceinline__ float fast_tanh(float x) { x = fminf(fmaxf(x, -15.f), 15.f); const float e = __expf(2.f * x); return (e - 1.f) / (e + 1.f); }
; __device__ __forceinline__ void p2_rwprep_tile(Frame& F, const Args& a, int t0) {
;     unsigned char* ws = a.ws;
;     const float* ZS = (const float*)(ws + WS_ZS);
;     LAS bf16* TD = (LAS bf16*)F.lds; LAS bf16* DA = TD + 32 * 64;
;     {
;         const int tok = F.tid >> 4, c4 = (F.tid & 15) * 4, t = t0 + tok;
;         const f32x4 zero = {0.f, 0.f, 0.f, 0.f};
;         const f32x4 cw = ld4(ZS + (size_t)t * 256 + c4), ca = ld4(ZS + (size_t)t * 256 + 64 + c4);
;         const f32x4 pw = t > 0 ? ld4(ZS + (size_t)(t - 1) * 256 + c4) : zero, pa = t > 0 ? ld4(ZS + (size_t)(t - 1) * 256 + 64 + c4) : zero;
;         const f32x4 mw = ld4(a.in[7] + c4), ma = ld4(a.in[8] + c4);
;         f32x4 dw = cw + (pw - cw) * mw, da = ca + (pa - ca) * ma;
;         dw.x = fast_tanh(dw.x); dw.y = fast_tanh(dw.y); dw.z = fast_tanh(dw.z); dw.w = fast_tanh(dw.w);
;         *(LAS v2u*)(TD + tok * 64 + c4) = pk4(dw); *(LAS v2u*)(DA + tok * 64 + c4) = pk4(da);
;     }
;     __syncthreads();
;     LAS unsigned char* lw_ = F.lds + 8192 + F.wave * 10240;
;     for (int q = 0; q < 4; ++q) { const int hh = q >> 1, rb = q & 1; rw_chunk_prep(a, 2 * F.wave + hh, t0 + rb * 16, TD + rb * 16 * 64, DA + rb * 16 * 64, lw_, F.lane); }
;     __syncthreads();
; }
; __global__ void __launch_bounds__(NTHR, 2) hybrid_fwd(Args args) {
;     ...
;         for (int tile = blockIdx.x; tile < T / 32; tile += F.G) p2_rwprep_tile(F, args, tile * 32); }
.Lrw_again:
	v_cmp_eq_u32_e64 s[22:23], 15, v11
	v_lshlrev_b32_e32 v6, 2, v10
	v_and_b32_e32 v1, 60, v6
	v_cndmask_b32_e64 v167, 0, 1.0, s[22:23]
	v_cmp_eq_u32_e64 s[22:23], 1, v11
	v_lshlrev_b32_e32 v66, 2, v1
	v_lshlrev_b32_e32 v2, 7, v64
	v_cndmask_b32_e64 v168, 0, 1.0, s[22:23]
	v_cmp_eq_u32_e64 s[22:23], 2, v11
	v_lshlrev_b32_e32 v1, 1, v1
	v_ashrrev_i32_e32 v4, 4, v10
	v_cndmask_b32_e64 v169, 0, 1.0, s[22:23]
	v_cmp_eq_u32_e64 s[22:23], 3, v11
	v_add3_u32 v65, 0, v2, v1
	v_lshlrev_b32_e32 v2, 3, v4
	v_cndmask_b32_e64 v170, 0, 1.0, s[22:23]
	v_cmp_eq_u32_e64 s[22:23], 4, v11
	v_ashrrev_i32_e32 v3, 31, v2
	v_mbcnt_hi_u32_b32 v1, -1, v156
	v_cndmask_b32_e64 v171, 0, 1.0, s[22:23]
	v_cmp_eq_u32_e64 s[22:23], 5, v11
	v_lshlrev_b64 v[2:3], 1, v[2:3]
	v_and_b32_e32 v1, 64, v1
	v_cndmask_b32_e64 v172, 0, 1.0, s[22:23]
	v_cmp_eq_u32_e64 s[22:23], 6, v11
	v_lshl_add_u64 v[74:75], s[6:7], 0, v[2:3]
	v_lshl_add_u64 v[76:77], s[8:9], 0, v[2:3]
	v_add_u32_e32 v2, 48, v10
	v_cndmask_b32_e64 v173, 0, 1.0, s[22:23]
	v_cmp_eq_u32_e64 s[22:23], 7, v11
	v_and_or_b32 v2, v2, 63, v1
	v_lshlrev_b32_e32 v158, 2, v2
	v_cndmask_b32_e64 v174, 0, 1.0, s[22:23]
	v_cmp_eq_u32_e64 s[22:23], 8, v11
	v_and_or_b32 v2, v10, 63, v1
	s_mul_i32 s0, s92, 0x2800
	v_cndmask_b32_e64 v175, 0, 1.0, s[22:23]
	v_cmp_eq_u32_e64 s[22:23], 9, v11
	v_lshlrev_b32_e32 v2, 2, v2
	s_add_i32 s33, s0, 0
	v_cndmask_b32_e64 v176, 0, 1.0, s[22:23]
	v_cmp_eq_u32_e64 s[22:23], 10, v11
	v_xor_b32_e32 v159, 0x80, v2
	v_or_b32_e32 v1, v1, v11
	v_mov_b32_e32 v2, 0xc0
	v_cndmask_b32_e64 v177, 0, 1.0, s[22:23]
	v_cmp_eq_u32_e64 s[22:23], 11, v11
	v_lshlrev_b32_e32 v157, 2, v4
	v_lshl_or_b32 v160, v1, 2, v2
	v_lshl_add_u32 v1, v11, 3, s33
	v_cndmask_b32_e64 v178, 0, 1.0, s[22:23]
	v_cmp_eq_u32_e64 s[22:23], 12, v11
	v_and_b32_e32 v7, -16, v10
	v_cmp_lt_i32_e64 s[4:5], 0, v4
	v_cmp_lt_i32_e64 s[6:7], 1, v4
	v_lshl_add_u32 v161, v4, 9, v1
	v_or_b32_e32 v2, 1, v157
	v_or_b32_e32 v3, 2, v157
	v_or_b32_e32 v4, 3, v157
	v_cndmask_b32_e64 v179, 0, 1.0, s[22:23]
	v_cmp_eq_u32_e64 s[22:23], 13, v11
	v_lshlrev_b32_e32 v5, 7, v11
	v_lshl_add_u32 v162, v2, 7, v1
	v_lshl_add_u32 v163, v3, 7, v1
	v_lshl_add_u32 v164, v4, 7, v1
	v_add_u32_e32 v1, s33, v7
	v_cndmask_b32_e64 v180, 0, 1.0, s[22:23]
	v_cmp_eq_u32_e64 s[22:23], 14, v11
	v_add_u32_e32 v165, v1, v5
	v_lshl_add_u32 v166, v11, 6, v1
	v_cndmask_b32_e64 v181, 0, 1.0, s[22:23]
	v_mov_b32_e32 v1, 0x3f80
	v_cmp_eq_u32_e64 s[22:23], v157, v11
	v_add3_u32 v155, 0, v5, v7
	v_cmp_lt_i32_e32 vcc, v2, v11
	v_cndmask_b32_e64 v5, 0, v1, s[22:23]
	v_cmp_eq_u32_e64 s[22:23], v2, v11
	v_mov_b32_e32 v67, 0
	v_cmp_lt_i32_e64 s[20:21], v3, v11
	v_cndmask_b32_e64 v2, 0, 1.0, s[22:23]
	v_cmp_eq_u32_e64 s[22:23], v3, v11
	v_or_b32_e32 v78, v2, v5
	v_cmp_gt_i32_e64 s[12:13], v3, v11
	v_cndmask_b32_e64 v1, 0, v1, s[22:23]
	v_cmp_eq_u32_e64 s[22:23], v4, v11
	v_lshl_add_u64 v[68:69], s[14:15], 0, v[66:67]
	v_cmp_lt_i32_e64 s[14:15], v4, v11
	v_cndmask_b32_e64 v2, 0, 1.0, s[22:23]
	v_or_b32_e32 v79, v1, v2
	v_lshlrev_b32_e32 v2, 3, v10
	v_ashrrev_i32_e32 v3, 31, v2
	v_cmp_gt_i32_e64 s[16:17], v4, v11
	v_lshl_add_u64 v[4:5], s[90:91], 0, v[2:3]
	s_mov_b64 s[2:3], 0x19000000
	s_lshl_b32 s34, s92, 1
	v_lshl_add_u64 v[80:81], v[4:5], 0, s[2:3]
	s_mov_b64 s[2:3], 0x1b000000
	s_add_u32 s35, s90, 0x3d00000
	v_lshl_add_u64 v[82:83], v[4:5], 0, s[2:3]
	v_lshl_add_u64 v[2:3], s[88:89], 0, v[2:3]
	s_mov_b64 s[2:3], 0x4000000
	v_lshl_add_u64 v[72:73], s[36:37], 0, v[66:67]
	s_addc_u32 s36, s91, 0
	v_lshl_add_u64 v[84:85], v[2:3], 0, s[2:3]
	s_mov_b64 s[2:3], 0x6000000
	v_ashrrev_i32_e32 v1, 31, v0
	v_lshl_add_u64 v[86:87], v[2:3], 0, s[2:3]
	s_mov_b64 s[2:3], 0x1d000000
	v_lshl_add_u64 v[90:91], s[88:89], 0, v[0:1]
	s_add_u32 s37, s90, 0x1f000000
	v_and_b32_e32 v0, 3, v10
	v_lshl_add_u64 v[88:89], v[4:5], 0, s[2:3]
	s_mov_b64 s[2:3], 0x2000000
	s_addc_u32 s40, s91, 0
	v_and_or_b32 v0, v6, 48, v0
	s_or_b64 s[20:21], s[14:15], s[20:21]
	v_lshl_add_u64 v[70:71], s[82:83], 0, v[66:67]
	s_mov_b32 s1, 0
	v_lshlrev_b32_e32 v154, 2, v11
	v_cmp_eq_u32_e64 s[24:25], 0, v11
	v_cmp_lt_i32_e64 s[8:9], v157, v11
	v_cmp_gt_i32_e64 s[10:11], v157, v11
	v_cmp_gt_u32_e64 s[18:19], 16, v10
	v_add_u32_e32 v182, s33, v6
	v_lshl_add_u64 v[92:93], v[90:91], 0, s[2:3]
	v_or3_b32 v94, v10, v6, 12
	v_mov_b32_e32 v95, v67
	s_mov_b32 s41, 0xc1700000
	s_movk_i32 s44, 0x1800
	s_movk_i32 s45, 0x1000
	s_mov_b32 s52, 0xbfb8aa3b
	s_mov_b32 s53, 0x800000
	s_mov_b32 s54, 0x3f317217
	s_mov_b32 s55, 0x7f800000
	v_lshlrev_b32_e32 v183, 2, v0
	v_mov_b32_e32 v184, 0x41700000
	v_mov_b32_e32 v185, 0x41b17218
	s_or_b64 s[22:23], s[20:21], vcc
	s_mov_b32 s99, s94
	s_cmp_eq_u32 s98, 1
	s_cbranch_scc0 .Lrw_u0
	s_add_i32 s99, s94, 0xc0
.Lrw_u0:
	s_lshr_b32 s56, s99, 1
	s_branch .LBB0_323
.LBB0_322:
	s_waitcnt vmcnt(0)
	s_barrier
	s_cmp_lg_u32 s98, 1
	s_cbranch_scc1 .Lrw_step
	s_cmp_lg_u32 s92, 0
	s_cbranch_scc1 .Lrw_step
	buffer_wbl2 sc1
	s_waitcnt vmcnt(0)
	s_lshl_b32 s101, s99, 2
	s_add_i32 s101, s101, 0x8000
	v_mov_b32_e32 v204, s101
	v_mov_b32_e32 v205, 1
	s_mov_b64 exec, 1
	global_atomic_add v204, v205, s[90:91]
	s_mov_b64 exec, -1
.Lrw_step:
	s_cmp_eq_u32 s98, 1
	s_cbranch_scc1 .Lrw_step1
	s_add_i32 s99, s99, s97
	s_cmpk_gt_i32 s99, 0xff
	s_cbranch_scc1 .LBB0_347
	s_lshr_b32 s56, s99, 1
	s_branch .LBB0_323
.Lrw_step1:
	s_add_i32 s101, s97, -64
	s_add_i32 s99, s99, s101
	s_cmpk_gt_i32 s99, 0x3ff
	s_cbranch_scc1 .LBB0_347
	s_lshr_b32 s56, s99, 1

; __device__ __forceinline__ void p2_rwprep_tile(Frame& F, const Args& a, int t0) {
;     ...
;     for (int q = 0; q < 4; ++q) { const int hh = q >> 1, rb = q & 1; rw_chunk_prep(a, 2 * F.wave + hh, t0 + rb * 16, TD + rb * 16 * 64, DA + rb * 16 * 64, lw_, F.lane); }
.LBB0_328:
	s_or_b64 exec, exec, s[26:27]
	s_waitcnt lgkmcnt(0)
	s_add_i32 s59, s59, 2
	s_add_i32 s58, s58, 32
	s_cmp_lt_u32 s59, 4
	s_cbranch_scc0 .LBB0_322

; #define SP_BAR() asm volatile("s_waitcnt lgkmcnt(0)\n\ts_barrier" ::: "memory")
; #define SP_WAIT() asm volatile("s_waitcnt vmcnt(36)" ::: "memory")
; __device__ __forceinline__ void p3_rwkv_state(Frame& F, const Args& a) {
;     ...
;     if (loader) {
;         DmaPtrs P; rw_dma_init(a, P, head, ib, lw, lane);
;         for (int n = 0; n < SP_D; ++n) rw_dma_issue(P, lw, lane, lds0 + (unsigned)(n % SP_R) * SP_SLOT);
;         SP_WAIT();
;         SP_BAR();
;         for (int n = 0; n < NC; n += 2) {
;             if (n + SP_D + 1 < NC) { rw_dma_issue(P, lw, lane, lds0 + (unsigned)((n + SP_D) % SP_R) * SP_SLOT); rw_dma_issue(P, lw, lane, lds0 + (unsigned)((n + SP_D + 1) % SP_R) * SP_SLOT); SP_WAIT(); }
;             else asm volatile("s_waitcnt vmcnt(0)" ::: "memory");
;             SP_BAR();
;         }
.Lscan_ldbig_chk:
	s_add_i32 s24, s18, 13
	s_cmp_lt_u32 s24, s17
	s_cbranch_scc1 .Lscan_ldbig_go
	v_add_u32_e32 v12, s17, v76
	v_lshlrev_b32_e32 v13, 2, v12
	v_add_u32_e32 v13, 0x8000, v13
	global_load_dword v13, v13, s[90:91] sc1
	s_movk_i32 s24, 0x3ff
	s_waitcnt vmcnt(0)
	v_cmp_ne_u32_e64 s[20:21], 0, v13
	v_cmp_lt_u32_e64 s[22:23], s24, v12
	s_nop 1
	s_or_b64 s[20:21], s[20:21], s[22:23]
	s_not_b64 s[20:21], s[20:21]
	s_ff1_i32_b64 s24, s[20:21]
	s_cmp_eq_u32 s24, -1
	s_cselect_b32 s24, 64, s24
	s_add_i32 s17, s17, s24
	s_cmp_lg_u32 s24, 0
	s_cbranch_scc1 .Lscan_ldbig_chk
	s_sleep 8
	s_branch .Lscan_ldbig_chk

; __global__ void __launch_bounds__(NTHR, 2) hybrid_fwd(Args args) {
;     ...
;     {   for (int g = blockIdx.x; g < T / 64; g += F.G) p2b_fgroup(F, args, g);
;     ...
;     {   if ((int)blockIdx.x < NRWB) p3_rwkv_state(F, args);
.Lfg_late_done:
	s_waitcnt vmcnt(0)
	s_barrier
	s_cmp_lg_u32 s92, 0
	s_cbranch_scc1 .Lfg_pub_skip
	buffer_wbl2 sc1
	s_waitcnt vmcnt(0)
	v_mov_b32_e32 v204, 0x9c00
	v_mov_b32_e32 v205, 1
	s_mov_b64 exec, 1
	global_atomic_add v204, v205, s[90:91]
	s_mov_b64 exec, -1

; __global__ void __launch_bounds__(NTHR, 2) hybrid_fwd(Args args) {
;     ...
;         const attn_body::bf16* ZBq = (const attn_body::bf16*)(ws + WS_ZB); attn_body::bf16* Yo = (attn_body::bf16*)(ws + WS_XN) + 1024; const float* F2 = (const float*)(ws + WS_F2);
;         float gapB; { const float bq = fabsf(args.in[19][F.lane]), bk = fabsf(args.in[20][F.lane]); float mq = bq, mk = bk;
; #pragma unroll
;             for (int o = 1; o < 64; o <<= 1) { mq = fmaxf(mq, __shfl_xor(mq, o)); mk = fmaxf(mk, __shfl_xor(mk, o)); }
;             const float gv_ = 2.f * (64.f * mq * mk * 0.125f * LOG2E * 1.03f) + 48.f; asm volatile("v_readfirstlane_b32 %0, %1" : "=s"(gapB) : "v"(gv_)); }
;         for (;;) {
.LBB0_457:
	s_cmp_lg_u32 s92, 0
	s_cbranch_scc1 .Lfg_wait_done
	s_sub_i32 s101, s97, 64
	v_mov_b32_e32 v204, 0x9c00
